# GQA loop: packed f32 row-sum adds split into scalar adds; diff loop: shorter row-max chain
# speedup vs baseline: 1.0493x; 1.0204x over previous
.Ldg_nb0_2:
	v_max3_f32 v64, v66, v67, v68
	v_max3_f32 v64, v64, v69, v70
	v_max3_f32 v64, v64, v71, v72
	v_max3_f32 v64, v64, v73, v74
	v_max3_f32 v64, v64, v75, v76
	v_max3_f32 v64, v64, v77, v78
	v_max3_f32 v64, v64, v79, v80
	v_max_f32_e32 v64, v64, v81
	v_mov_b32_e32 v65, v64
	s_nop 1
	v_permlane32_swap_b32_e32 v64, v65
	v_max_f32_e32 v64, v64, v65
	v_cmp_lt_f32_e32 vcc, s97, v64
	s_cbranch_vccnz .Ldg_rare0_2

.Ldg_nb1_3:
	v_max3_f32 v64, v236, v237, v238
	v_max3_f32 v64, v64, v239, v240
	v_max3_f32 v64, v64, v241, v242
	v_max3_f32 v64, v64, v243, v244
	v_max3_f32 v64, v64, v245, v246
	v_max3_f32 v64, v64, v247, v248
	v_max3_f32 v64, v64, v249, v250
	v_max_f32_e32 v64, v64, v251
	v_mov_b32_e32 v65, v64
	s_nop 1
	v_permlane32_swap_b32_e32 v64, v65
	v_max_f32_e32 v64, v64, v65
	v_cmp_lt_f32_e32 vcc, s97, v64
	s_cbranch_vccnz .Ldg_rare1_3
	s_waitcnt lgkmcnt(3)
	v_mfma_f32_32x32x16_bf16 v[32:47], v[200:203], v[130:133], v[32:47]
	ds_read_b128 v[126:129], v195 offset:16384
	ds_read_b128 v[114:117], v195 offset:20480
	v_exp_f32_e32 v236, v236
	v_exp_f32_e32 v237, v237
	v_exp_f32_e32 v238, v238
	s_waitcnt lgkmcnt(4)
	v_mfma_f32_32x32x16_bf16 v[48:63], v[200:203], v[134:137], v[48:63]
	ds_read_b128 v[122:125], v196 offset:16384
	ds_read_b128 v[118:121], v196 offset:20480
	v_exp_f32_e32 v239, v239
	v_exp_f32_e32 v240, v240
	v_exp_f32_e32 v241, v241
	s_waitcnt lgkmcnt(5)
	v_mfma_f32_32x32x16_bf16 v[32:47], v[204:207], v[138:141], v[32:47]
	v_exp_f32_e32 v242, v242
	v_exp_f32_e32 v243, v243
	v_exp_f32_e32 v244, v244
	s_waitcnt lgkmcnt(4)
	v_mfma_f32_32x32x16_bf16 v[48:63], v[204:207], v[142:145], v[48:63]
	v_exp_f32_e32 v245, v245
	v_exp_f32_e32 v246, v246
	v_exp_f32_e32 v247, v247
	v_exp_f32_e32 v248, v248
	v_exp_f32_e32 v249, v249
	v_exp_f32_e32 v250, v250
	v_exp_f32_e32 v251, v251
	v_cvt_pk_bf16_f32 v160, v236, v237
	v_cvt_pk_bf16_f32 v161, v238, v239
	v_cvt_pk_bf16_f32 v162, v240, v241
	v_cvt_pk_bf16_f32 v163, v242, v243
	v_cvt_pk_bf16_f32 v164, v244, v245
	v_cvt_pk_bf16_f32 v165, v246, v247
	v_cvt_pk_bf16_f32 v166, v248, v249
	v_cvt_pk_bf16_f32 v167, v250, v251

.Ldg_nb1_6:
	v_max3_f32 v64, v236, v237, v238
	v_max3_f32 v64, v64, v239, v240
	v_max3_f32 v64, v64, v241, v242
	v_max3_f32 v64, v64, v243, v244
	v_max3_f32 v64, v64, v245, v246
	v_max3_f32 v64, v64, v247, v248
	v_max3_f32 v64, v64, v249, v250
	v_max_f32_e32 v64, v64, v251
	v_mov_b32_e32 v65, v64
	s_nop 1
	v_permlane32_swap_b32_e32 v64, v65
	v_max_f32_e32 v64, v64, v65
	v_cmp_lt_f32_e32 vcc, s97, v64
	s_cbranch_vccnz .Ldg_rare1_6
	s_waitcnt lgkmcnt(3)
	v_mfma_f32_32x32x16_bf16 v[32:47], v[200:203], v[130:133], v[32:47]
	ds_read_b128 v[126:129], v195 offset:49152
	ds_read_b128 v[114:117], v195 offset:53248
	v_exp_f32_e32 v236, v236
	v_exp_f32_e32 v237, v237
	v_exp_f32_e32 v238, v238
	s_waitcnt lgkmcnt(4)
	v_mfma_f32_32x32x16_bf16 v[48:63], v[200:203], v[134:137], v[48:63]
	ds_read_b128 v[122:125], v196 offset:49152
	ds_read_b128 v[118:121], v196 offset:53248
	v_exp_f32_e32 v239, v239
	v_exp_f32_e32 v240, v240
	v_exp_f32_e32 v241, v241
	s_waitcnt lgkmcnt(5)
	v_mfma_f32_32x32x16_bf16 v[32:47], v[204:207], v[138:141], v[32:47]
	v_exp_f32_e32 v242, v242
	v_exp_f32_e32 v243, v243
	v_exp_f32_e32 v244, v244
	s_waitcnt lgkmcnt(4)
	v_mfma_f32_32x32x16_bf16 v[48:63], v[204:207], v[142:145], v[48:63]
	v_exp_f32_e32 v245, v245
	v_exp_f32_e32 v246, v246
	v_exp_f32_e32 v247, v247
	v_exp_f32_e32 v248, v248
	v_exp_f32_e32 v249, v249
	v_exp_f32_e32 v250, v250
	v_exp_f32_e32 v251, v251
	v_cvt_pk_bf16_f32 v160, v236, v237
	v_cvt_pk_bf16_f32 v161, v238, v239
	v_cvt_pk_bf16_f32 v162, v240, v241
	v_cvt_pk_bf16_f32 v163, v242, v243
	v_cvt_pk_bf16_f32 v164, v244, v245
	v_cvt_pk_bf16_f32 v165, v246, v247
	v_cvt_pk_bf16_f32 v166, v248, v249
	v_cvt_pk_bf16_f32 v167, v250, v251

.Ldg_nb1_11:
	v_max3_f32 v64, v236, v237, v238
	v_max3_f32 v64, v64, v239, v240
	v_max3_f32 v64, v64, v241, v242
	v_max3_f32 v64, v64, v243, v244
	v_max3_f32 v64, v64, v245, v246
	v_max3_f32 v64, v64, v247, v248
	v_max3_f32 v64, v64, v249, v250
	v_max_f32_e32 v64, v64, v251
	v_mov_b32_e32 v65, v64
	s_nop 1
	v_permlane32_swap_b32_e32 v64, v65
	v_max_f32_e32 v64, v64, v65
	v_cmp_lt_f32_e32 vcc, s97, v64
	s_cbranch_vccnz .Ldg_rare1_11
	v_mfma_f32_32x32x16_bf16 v[32:47], v[200:203], v[130:133], v[32:47]
	ds_read_b128 v[126:129], v195 offset:16384
	ds_read_b128 v[114:117], v195 offset:20480
	v_exp_f32_e32 v236, v236
	v_exp_f32_e32 v237, v237
	v_exp_f32_e32 v238, v238
	v_mfma_f32_32x32x16_bf16 v[48:63], v[200:203], v[134:137], v[48:63]
	ds_read_b128 v[122:125], v196 offset:16384
	ds_read_b128 v[118:121], v196 offset:20480
	v_exp_f32_e32 v239, v239
	v_exp_f32_e32 v240, v240
	v_exp_f32_e32 v241, v241
	v_mfma_f32_32x32x16_bf16 v[32:47], v[204:207], v[138:141], v[32:47]
	v_exp_f32_e32 v242, v242
	v_exp_f32_e32 v243, v243
	v_exp_f32_e32 v244, v244
	v_mfma_f32_32x32x16_bf16 v[48:63], v[204:207], v[142:145], v[48:63]
	v_exp_f32_e32 v245, v245
	v_exp_f32_e32 v246, v246
	v_exp_f32_e32 v247, v247
	v_exp_f32_e32 v248, v248
	v_exp_f32_e32 v249, v249
	v_exp_f32_e32 v250, v250
	v_exp_f32_e32 v251, v251
	v_cvt_pk_bf16_f32 v160, v236, v237
	v_cvt_pk_bf16_f32 v161, v238, v239
	v_cvt_pk_bf16_f32 v162, v240, v241
	v_cvt_pk_bf16_f32 v163, v242, v243
	v_cvt_pk_bf16_f32 v164, v244, v245
	v_cvt_pk_bf16_f32 v165, v246, v247
	v_cvt_pk_bf16_f32 v166, v248, v249
	v_cvt_pk_bf16_f32 v167, v250, v251

.Ldg_nb1_14:
	v_max3_f32 v64, v236, v237, v238
	v_max3_f32 v64, v64, v239, v240
	v_max3_f32 v64, v64, v241, v242
	v_max3_f32 v64, v64, v243, v244
	v_max3_f32 v64, v64, v245, v246
	v_max3_f32 v64, v64, v247, v248
	v_max3_f32 v64, v64, v249, v250
	v_max_f32_e32 v64, v64, v251
	v_mov_b32_e32 v65, v64
	s_nop 1
	v_permlane32_swap_b32_e32 v64, v65
	v_max_f32_e32 v64, v64, v65
	v_cmp_lt_f32_e32 vcc, s97, v64
	s_cbranch_vccnz .Ldg_rare1_14
	v_mfma_f32_32x32x16_bf16 v[32:47], v[200:203], v[130:133], v[32:47]
	ds_read_b128 v[126:129], v195 offset:49152
	ds_read_b128 v[114:117], v195 offset:53248
	v_exp_f32_e32 v236, v236
	v_exp_f32_e32 v237, v237
	v_exp_f32_e32 v238, v238
	v_mfma_f32_32x32x16_bf16 v[48:63], v[200:203], v[134:137], v[48:63]
	ds_read_b128 v[122:125], v196 offset:49152
	ds_read_b128 v[118:121], v196 offset:53248
	v_exp_f32_e32 v239, v239
	v_exp_f32_e32 v240, v240
	v_exp_f32_e32 v241, v241
	v_mfma_f32_32x32x16_bf16 v[32:47], v[204:207], v[138:141], v[32:47]
	v_exp_f32_e32 v242, v242
	v_exp_f32_e32 v243, v243
	v_exp_f32_e32 v244, v244
	v_mfma_f32_32x32x16_bf16 v[48:63], v[204:207], v[142:145], v[48:63]
	v_exp_f32_e32 v245, v245
	v_exp_f32_e32 v246, v246
	v_exp_f32_e32 v247, v247
	v_exp_f32_e32 v248, v248
	v_exp_f32_e32 v249, v249
	v_exp_f32_e32 v250, v250
	v_exp_f32_e32 v251, v251
	v_cvt_pk_bf16_f32 v160, v236, v237
	v_cvt_pk_bf16_f32 v161, v238, v239
	v_cvt_pk_bf16_f32 v162, v240, v241
	v_cvt_pk_bf16_f32 v163, v242, v243
	v_cvt_pk_bf16_f32 v164, v244, v245
	v_cvt_pk_bf16_f32 v165, v246, v247
	v_cvt_pk_bf16_f32 v166, v248, v249
	v_cvt_pk_bf16_f32 v167, v250, v251

.LBB0_301:
	v_exp_f32_e32 v80, v80
	v_exp_f32_e32 v81, v81
	v_exp_f32_e32 v82, v82
	v_exp_f32_e32 v83, v83
	v_exp_f32_e32 v154, v84
	v_exp_f32_e32 v155, v85
	v_exp_f32_e32 v156, v86
	v_exp_f32_e32 v157, v87
	v_exp_f32_e32 v84, v88
	v_exp_f32_e32 v85, v89
	v_exp_f32_e32 v86, v90
	v_exp_f32_e32 v87, v91
	v_exp_f32_e32 v88, v92
	v_exp_f32_e32 v89, v93
	v_add_f32_e32 v92, v82, v80
	v_add_f32_e32 v93, v83, v81
	v_exp_f32_e32 v90, v94
	v_add_f32_e32 v92, v154, v92
	v_add_f32_e32 v93, v155, v93
	v_exp_f32_e32 v91, v95
	v_add_f32_e32 v92, v156, v92
	v_add_f32_e32 v93, v157, v93
	v_exp_f32_e32 v64, v64
	v_add_f32_e32 v92, v84, v92
	v_add_f32_e32 v93, v85, v93
	v_exp_f32_e32 v65, v65
	v_add_f32_e32 v92, v86, v92
	v_add_f32_e32 v93, v87, v93
	v_exp_f32_e32 v66, v66
	v_exp_f32_e32 v67, v67
	v_add_f32_e32 v92, v88, v92
	v_add_f32_e32 v93, v89, v93
	v_cvt_pk_bf16_f32 v84, v84, v85
	v_cvt_pk_bf16_f32 v85, v86, v87
	v_cvt_pk_bf16_f32 v86, v88, v89
	v_exp_f32_e32 v88, v68
	v_exp_f32_e32 v89, v69
	v_add_f32_e32 v92, v90, v92
	v_add_f32_e32 v93, v91, v93
	v_cvt_pk_bf16_f32 v87, v90, v91
	v_exp_f32_e32 v90, v70
	v_exp_f32_e32 v91, v71
	v_exp_f32_e32 v68, v72
	v_exp_f32_e32 v69, v73
	v_exp_f32_e32 v70, v74
	v_exp_f32_e32 v71, v75
	v_exp_f32_e32 v72, v76
	v_exp_f32_e32 v73, v77
	v_add_f32_e32 v76, v64, v66
	v_add_f32_e32 v77, v65, v67
	v_exp_f32_e32 v74, v78
	v_add_f32_e32 v76, v88, v76
	v_add_f32_e32 v77, v89, v77
	v_exp_f32_e32 v75, v79
	v_add_f32_e32 v76, v90, v76
	v_add_f32_e32 v77, v91, v77
	v_add_f32_e32 v92, v92, v93
	v_add_f32_e32 v76, v68, v76
	v_add_f32_e32 v77, v69, v77
	v_add_f32_e32 v173, v233, v92
	v_add_f32_e32 v76, v70, v76
	v_add_f32_e32 v77, v71, v77
	v_cvt_pk_bf16_f32 v80, v80, v81
	v_add_f32_e32 v76, v72, v76
	v_add_f32_e32 v77, v73, v77
	v_cvt_pk_bf16_f32 v81, v82, v83
	v_add_f32_e32 v76, v74, v76
	v_add_f32_e32 v77, v75, v77
	v_cvt_pk_bf16_f32 v82, v154, v155
	v_add_f32_e32 v76, v76, v77
	v_add_f32_e32 v202, v152, v76
	v_cvt_pk_bf16_f32 v83, v156, v157
	v_cvt_pk_bf16_f32 v64, v64, v65
	v_cvt_pk_bf16_f32 v68, v68, v69
	v_cvt_pk_bf16_f32 v65, v66, v67
	v_cvt_pk_bf16_f32 v69, v70, v71
	v_cvt_pk_bf16_f32 v66, v88, v89
	v_cvt_pk_bf16_f32 v70, v72, v73
	v_cvt_pk_bf16_f32 v67, v90, v91
	v_cvt_pk_bf16_f32 v71, v74, v75
	s_setprio 1
	s_waitcnt lgkmcnt(3)
	v_mfma_f32_32x32x16_bf16 v[48:63], v[80:83], v[104:107], v[48:63]
	s_waitcnt lgkmcnt(2)
	v_mfma_f32_32x32x16_bf16 v[32:47], v[80:83], v[96:99], v[32:47]
	v_mfma_f32_32x32x16_bf16 v[16:31], v[64:67], v[104:107], v[16:31]
	v_mfma_f32_32x32x16_bf16 v[0:15], v[64:67], v[96:99], v[0:15]
	s_waitcnt lgkmcnt(1)
	v_mfma_f32_32x32x16_bf16 v[48:63], v[84:87], v[108:111], v[48:63]
	s_waitcnt lgkmcnt(0)
	v_mfma_f32_32x32x16_bf16 v[32:47], v[84:87], v[100:103], v[32:47]
	v_mfma_f32_32x32x16_bf16 v[16:31], v[68:71], v[108:111], v[16:31]
	v_mfma_f32_32x32x16_bf16 v[0:15], v[68:71], v[100:103], v[0:15]
	s_setprio 0
	v_lshl_add_u64 v[194:195], v[194:195], 0, s[94:95]
	v_lshl_add_u64 v[196:197], v[196:197], 0, s[84:85]
	s_andn2_b64 vcc, exec, s[4:5]
	s_add_i32 s45, s45, 2
	s_cbranch_vccz .LBB0_295

.LBB0_318:
	v_exp_f32_e32 v80, v80
	v_exp_f32_e32 v81, v81
	v_exp_f32_e32 v82, v82
	v_exp_f32_e32 v83, v83
	v_exp_f32_e32 v84, v84
	v_exp_f32_e32 v85, v85
	v_exp_f32_e32 v86, v86
	v_exp_f32_e32 v87, v87
	v_exp_f32_e32 v88, v88
	v_exp_f32_e32 v89, v89
	v_exp_f32_e32 v90, v90
	v_exp_f32_e32 v91, v91
	v_add_f32_e32 v174, v82, v80
	v_add_f32_e32 v175, v83, v81
	v_exp_f32_e32 v92, v92
	v_exp_f32_e32 v93, v93
	v_add_f32_e32 v174, v84, v174
	v_add_f32_e32 v175, v85, v175
	v_exp_f32_e32 v94, v94
	v_exp_f32_e32 v95, v95
	v_add_f32_e32 v174, v86, v174
	v_add_f32_e32 v175, v87, v175
	v_exp_f32_e32 v176, v68
	v_add_f32_e32 v174, v88, v174
	v_add_f32_e32 v175, v89, v175
	v_exp_f32_e32 v177, v69
	v_add_f32_e32 v174, v90, v174
	v_add_f32_e32 v175, v91, v175
	v_exp_f32_e32 v178, v70
	v_add_f32_e32 v174, v92, v174
	v_add_f32_e32 v175, v93, v175
	v_exp_f32_e32 v179, v71
	v_add_f32_e32 v174, v94, v174
	v_add_f32_e32 v175, v95, v175
	v_exp_f32_e32 v180, v72
	v_add_f32_e32 v172, v174, v175
	v_add_f32_e32 v232, v173, v172
	v_exp_f32_e32 v172, v64
	v_exp_f32_e32 v173, v65
	v_exp_f32_e32 v174, v66
	v_exp_f32_e32 v175, v67
	v_exp_f32_e32 v181, v73
	v_exp_f32_e32 v182, v74
	v_exp_f32_e32 v183, v75
	v_exp_f32_e32 v198, v76
	v_exp_f32_e32 v199, v77
	v_exp_f32_e32 v200, v78
	v_exp_f32_e32 v201, v79
	v_cvt_pk_bf16_f32 v204, v80, v81
	v_cvt_pk_bf16_f32 v208, v88, v89
	v_cvt_pk_bf16_f32 v205, v82, v83
	v_cvt_pk_bf16_f32 v209, v90, v91
	v_cvt_pk_bf16_f32 v206, v84, v85
	v_cvt_pk_bf16_f32 v210, v92, v93
	v_cvt_pk_bf16_f32 v207, v86, v87
	v_cvt_pk_bf16_f32 v211, v94, v95
	v_cvt_pk_bf16_f32 v234, v172, v173
	v_cvt_pk_bf16_f32 v238, v180, v181
	v_cvt_pk_bf16_f32 v235, v174, v175
	v_cvt_pk_bf16_f32 v239, v182, v183
	v_cvt_pk_bf16_f32 v236, v176, v177
	v_cvt_pk_bf16_f32 v240, v198, v199
	v_cvt_pk_bf16_f32 v237, v178, v179
	v_cvt_pk_bf16_f32 v241, v200, v201
	v_xor_b32_e32 v80, 0x80000000, v231
	v_xor_b32_e32 v64, 0x80000000, v223
	s_setprio 1
	v_mov_b32_e32 v81, v80
	v_mov_b32_e32 v82, v80
	v_mov_b32_e32 v83, v80
	v_mov_b32_e32 v84, v80
	v_mov_b32_e32 v85, v80
	v_mov_b32_e32 v86, v80
	v_mov_b32_e32 v87, v80
	v_mov_b32_e32 v88, v80
	v_mov_b32_e32 v89, v80
	v_mov_b32_e32 v90, v80
	v_mov_b32_e32 v91, v80
	v_mov_b32_e32 v92, v80
	v_mov_b32_e32 v93, v80
	v_mov_b32_e32 v94, v80
	v_mov_b32_e32 v95, v80
	v_mov_b32_e32 v65, v64
	v_mov_b32_e32 v66, v64
	v_mov_b32_e32 v67, v64
	v_mov_b32_e32 v68, v64
	v_mov_b32_e32 v69, v64
	v_mov_b32_e32 v70, v64
	v_mov_b32_e32 v71, v64
	v_mov_b32_e32 v72, v64
	v_mov_b32_e32 v73, v64
	v_mov_b32_e32 v74, v64
	v_mov_b32_e32 v75, v64
	v_mov_b32_e32 v76, v64
	v_mov_b32_e32 v77, v64
	v_mov_b32_e32 v78, v64
	v_mov_b32_e32 v79, v64
	s_waitcnt lgkmcnt(5)
	v_mfma_f32_32x32x16_bf16 v[80:95], v[160:163], v[112:115], v[80:95]
	v_mfma_f32_32x32x16_bf16 v[64:79], v[160:163], v[132:135], v[64:79]
	s_waitcnt lgkmcnt(3)
	v_mfma_f32_32x32x16_bf16 v[80:95], v[164:167], v[116:119], v[80:95]
	v_mfma_f32_32x32x16_bf16 v[64:79], v[164:167], v[136:139], v[64:79]
	v_mfma_f32_32x32x16_bf16 v[80:95], v[156:159], v[124:127], v[80:95]
	v_mfma_f32_32x32x16_bf16 v[64:79], v[156:159], v[140:143], v[64:79]
	v_mfma_f32_32x32x16_bf16 v[80:95], v[152:155], v[128:131], v[80:95]
	v_mfma_f32_32x32x16_bf16 v[64:79], v[152:155], v[144:147], v[64:79]
	s_setprio 0
	s_setprio 1
	v_mfma_f32_32x32x16_bf16 v[48:63], v[204:207], v[104:107], v[48:63]
	s_waitcnt lgkmcnt(2)
	v_mfma_f32_32x32x16_bf16 v[32:47], v[204:207], v[96:99], v[32:47]
	v_mfma_f32_32x32x16_bf16 v[16:31], v[234:237], v[104:107], v[16:31]
	v_mfma_f32_32x32x16_bf16 v[0:15], v[234:237], v[96:99], v[0:15]
	s_waitcnt lgkmcnt(1)
	v_mfma_f32_32x32x16_bf16 v[48:63], v[208:211], v[108:111], v[48:63]
	s_waitcnt lgkmcnt(0)
	v_mfma_f32_32x32x16_bf16 v[32:47], v[208:211], v[100:103], v[32:47]
	v_mfma_f32_32x32x16_bf16 v[16:31], v[238:241], v[108:111], v[16:31]
	v_mfma_f32_32x32x16_bf16 v[0:15], v[238:241], v[100:103], v[0:15]
	s_setprio 0
	ds_read_b128 v[104:107], v229 offset:8192
	ds_read_b128 v[96:99], v229 offset:12288
	ds_read_b128 v[108:111], v230 offset:8192
	ds_read_b128 v[100:103], v230 offset:12288
	v_max_f32_e32 v152, v81, v81
	v_max_f32_e32 v153, v80, v80
	v_max_f32_e32 v152, v153, v152
	v_max3_f32 v152, v152, v82, v83
	v_max3_f32 v152, v152, v84, v85
	v_max3_f32 v152, v152, v86, v87
	v_max3_f32 v152, v152, v88, v89
	v_max3_f32 v152, v152, v90, v91
	v_max3_f32 v152, v152, v92, v93
	v_max3_f32 v152, v152, v94, v95
	v_mov_b32_e32 v153, v152
	s_nop 1
	v_permlane32_swap_b32_e32 v152, v153
	v_max_f32_e32 v153, v153, v153
	v_max_f32_e32 v152, v152, v152
	v_max_f32_e32 v152, v152, v153
	v_cmp_lt_f32_e32 vcc, s97, v152
	s_cbranch_vccz .LBB0_320
	v_max_f32_e32 v152, v152, v152
	v_max_f32_e32 v152, 0, v152
	v_add_f32_e32 v231, v231, v152
	v_pk_add_f32 v[80:81], v[80:81], v[152:153] op_sel_hi:[1,0] neg_lo:[0,1] neg_hi:[0,1]
	v_pk_add_f32 v[82:83], v[82:83], v[152:153] op_sel_hi:[1,0] neg_lo:[0,1] neg_hi:[0,1]
	v_pk_add_f32 v[84:85], v[84:85], v[152:153] op_sel_hi:[1,0] neg_lo:[0,1] neg_hi:[0,1]
	v_pk_add_f32 v[86:87], v[86:87], v[152:153] op_sel_hi:[1,0] neg_lo:[0,1] neg_hi:[0,1]
	v_pk_add_f32 v[88:89], v[88:89], v[152:153] op_sel_hi:[1,0] neg_lo:[0,1] neg_hi:[0,1]
	v_pk_add_f32 v[90:91], v[90:91], v[152:153] op_sel_hi:[1,0] neg_lo:[0,1] neg_hi:[0,1]
	v_pk_add_f32 v[92:93], v[92:93], v[152:153] op_sel_hi:[1,0] neg_lo:[0,1] neg_hi:[0,1]
	v_pk_add_f32 v[94:95], v[94:95], v[152:153] op_sel_hi:[1,0] neg_lo:[0,1] neg_hi:[0,1]
	v_exp_f32_e64 v152, -v152
	ds_write_b32 v222, v152
	v_mul_f32_e32 v232, v232, v152
	ds_read_b128 v[152:155], v221
	ds_read_b128 v[156:159], v221 offset:32
	ds_read_b128 v[160:163], v221 offset:64
	ds_read_b128 v[164:167], v221 offset:96
	s_waitcnt lgkmcnt(3)
	v_pk_mul_f32 v[50:51], v[50:51], v[154:155]
	s_waitcnt lgkmcnt(2)
	v_pk_mul_f32 v[54:55], v[54:55], v[158:159]
	s_waitcnt lgkmcnt(1)
	v_pk_mul_f32 v[58:59], v[58:59], v[162:163]
	s_waitcnt lgkmcnt(0)
	v_pk_mul_f32 v[62:63], v[62:63], v[166:167]
	v_pk_mul_f32 v[60:61], v[60:61], v[164:165]
	v_pk_mul_f32 v[56:57], v[56:57], v[160:161]
	v_pk_mul_f32 v[52:53], v[52:53], v[156:157]
	v_pk_mul_f32 v[48:49], v[48:49], v[152:153]
	v_pk_mul_f32 v[46:47], v[46:47], v[166:167]
	v_pk_mul_f32 v[42:43], v[42:43], v[162:163]
	v_pk_mul_f32 v[38:39], v[38:39], v[158:159]
	v_pk_mul_f32 v[34:35], v[34:35], v[154:155]
	v_pk_mul_f32 v[44:45], v[44:45], v[164:165]
	v_pk_mul_f32 v[40:41], v[40:41], v[160:161]
	v_pk_mul_f32 v[36:37], v[36:37], v[156:157]
	v_pk_mul_f32 v[32:33], v[32:33], v[152:153]
.LBB0_320:
	v_add_f32_e32 v152, v172, v174
	v_add_f32_e32 v153, v173, v175
	s_nop 0
	v_add_f32_e32 v152, v176, v152
	v_add_f32_e32 v153, v177, v153
	s_nop 0
	v_add_f32_e32 v152, v178, v152
	v_add_f32_e32 v153, v179, v153
	s_nop 0
	v_add_f32_e32 v152, v180, v152
	v_add_f32_e32 v153, v181, v153
	s_nop 0
	v_add_f32_e32 v152, v182, v152
	v_add_f32_e32 v153, v183, v153
	s_nop 0
	v_add_f32_e32 v152, v198, v152
	v_add_f32_e32 v153, v199, v153
	s_nop 0
	v_add_f32_e32 v152, v200, v152
	v_add_f32_e32 v153, v201, v153
	s_nop 0
	v_add_f32_e32 v152, v152, v153
	v_add_f32_e32 v233, v202, v152
	v_max_f32_e32 v152, v65, v65
	v_max_f32_e32 v153, v64, v64
	v_max_f32_e32 v152, v153, v152
	v_max3_f32 v152, v152, v66, v67
	v_max3_f32 v152, v152, v68, v69
	v_max3_f32 v152, v152, v70, v71
	v_max3_f32 v152, v152, v72, v73
	v_max3_f32 v152, v152, v74, v75
	v_max3_f32 v152, v152, v76, v77
	v_max3_f32 v152, v152, v78, v79
	v_mov_b32_e32 v153, v152
	s_nop 1
	v_permlane32_swap_b32_e32 v152, v153
	v_max_f32_e32 v153, v153, v153
	v_max_f32_e32 v152, v152, v152
	v_max_f32_e32 v152, v152, v153
	v_cmp_lt_f32_e32 vcc, s97, v152
	s_cbranch_vccz .LBB0_322
	v_max_f32_e32 v152, v152, v152
	v_max_f32_e32 v152, 0, v152
	v_add_f32_e32 v223, v223, v152
	v_pk_add_f32 v[64:65], v[64:65], v[152:153] op_sel_hi:[1,0] neg_lo:[0,1] neg_hi:[0,1]
	v_pk_add_f32 v[66:67], v[66:67], v[152:153] op_sel_hi:[1,0] neg_lo:[0,1] neg_hi:[0,1]
	v_pk_add_f32 v[68:69], v[68:69], v[152:153] op_sel_hi:[1,0] neg_lo:[0,1] neg_hi:[0,1]
	v_pk_add_f32 v[70:71], v[70:71], v[152:153] op_sel_hi:[1,0] neg_lo:[0,1] neg_hi:[0,1]
	v_pk_add_f32 v[72:73], v[72:73], v[152:153] op_sel_hi:[1,0] neg_lo:[0,1] neg_hi:[0,1]
	v_pk_add_f32 v[74:75], v[74:75], v[152:153] op_sel_hi:[1,0] neg_lo:[0,1] neg_hi:[0,1]
	v_pk_add_f32 v[76:77], v[76:77], v[152:153] op_sel_hi:[1,0] neg_lo:[0,1] neg_hi:[0,1]
	v_pk_add_f32 v[78:79], v[78:79], v[152:153] op_sel_hi:[1,0] neg_lo:[0,1] neg_hi:[0,1]
	v_exp_f32_e64 v152, -v152
	ds_write_b32 v222, v152
	v_mul_f32_e32 v233, v233, v152
	ds_read_b128 v[152:155], v221
	ds_read_b128 v[156:159], v221 offset:32
	ds_read_b128 v[160:163], v221 offset:64
	ds_read_b128 v[164:167], v221 offset:96
	s_waitcnt lgkmcnt(3)
	v_pk_mul_f32 v[18:19], v[18:19], v[154:155]
	s_waitcnt lgkmcnt(2)
	v_pk_mul_f32 v[22:23], v[22:23], v[158:159]
	s_waitcnt lgkmcnt(1)
	v_pk_mul_f32 v[26:27], v[26:27], v[162:163]
	s_waitcnt lgkmcnt(0)
	v_pk_mul_f32 v[30:31], v[30:31], v[166:167]
	v_pk_mul_f32 v[28:29], v[28:29], v[164:165]
	v_pk_mul_f32 v[24:25], v[24:25], v[160:161]
	v_pk_mul_f32 v[20:21], v[20:21], v[156:157]
	v_pk_mul_f32 v[16:17], v[16:17], v[152:153]
	v_pk_mul_f32 v[14:15], v[14:15], v[166:167]
	v_pk_mul_f32 v[10:11], v[10:11], v[162:163]
	v_pk_mul_f32 v[6:7], v[6:7], v[158:159]
	v_pk_mul_f32 v[2:3], v[2:3], v[154:155]
	v_pk_mul_f32 v[12:13], v[12:13], v[164:165]
	v_pk_mul_f32 v[8:9], v[8:9], v[160:161]
	v_pk_mul_f32 v[4:5], v[4:5], v[156:157]
	v_pk_mul_f32 v[0:1], v[0:1], v[152:153]

.LBB0_324:
	v_add_f32_e32 v64, v82, v80
	v_add_f32_e32 v65, v83, v81
	ds_read_b128 v[152:155], v227 offset:16384
	ds_read_b128 v[156:159], v228 offset:16384
	ds_read_b128 v[160:163], v229 offset:16384
	ds_read_b128 v[164:167], v230 offset:16384
	v_add_f32_e32 v64, v84, v64
	v_add_f32_e32 v65, v85, v65
	v_xor_b32_e32 v96, 0x80000000, v231
	v_add_f32_e32 v64, v86, v64
	v_add_f32_e32 v65, v87, v65
	s_nop 0
	v_add_f32_e32 v64, v88, v64
	v_add_f32_e32 v65, v89, v65
	s_nop 0
	v_add_f32_e32 v64, v90, v64
	v_add_f32_e32 v65, v91, v65
	s_nop 0
	v_add_f32_e32 v64, v92, v64
	v_add_f32_e32 v65, v93, v65
	s_nop 0
	v_add_f32_e32 v64, v94, v64
	v_add_f32_e32 v65, v95, v65
	s_nop 0
	v_add_f32_e32 v64, v64, v65
	v_add_f32_e32 v234, v232, v64
	v_xor_b32_e32 v64, 0x80000000, v223
	s_setprio 1
	v_mov_b32_e32 v78, v64
	v_mov_b32_e32 v79, v64
	v_mov_b32_e32 v65, v64
	v_mov_b32_e32 v66, v64
	v_mov_b32_e32 v67, v64
	v_mov_b32_e32 v68, v64
	v_mov_b32_e32 v69, v64
	v_mov_b32_e32 v70, v64
	v_mov_b32_e32 v71, v64
	v_mov_b32_e32 v72, v64
	v_mov_b32_e32 v73, v64
	v_mov_b32_e32 v74, v64
	v_mov_b32_e32 v75, v64
	v_mov_b32_e32 v76, v64
	v_mov_b32_e32 v77, v64
	v_mov_b64_e32 v[94:95], v[78:79]
	v_mov_b32_e32 v97, v96
	v_mov_b32_e32 v98, v96
	v_mov_b32_e32 v99, v96
	v_mov_b32_e32 v100, v96
	v_mov_b32_e32 v101, v96
	v_mov_b32_e32 v102, v96
	v_mov_b32_e32 v103, v96
	v_mov_b32_e32 v104, v96
	v_mov_b32_e32 v105, v96
	v_mov_b32_e32 v106, v96
	v_mov_b32_e32 v107, v96
	v_mov_b32_e32 v108, v96
	v_mov_b32_e32 v109, v96
	v_mov_b32_e32 v110, v96
	v_mov_b32_e32 v111, v96
	v_mov_b64_e32 v[92:93], v[76:77]
	v_mov_b64_e32 v[90:91], v[74:75]
	v_mov_b64_e32 v[88:89], v[72:73]
	v_mov_b64_e32 v[86:87], v[70:71]
	v_mov_b64_e32 v[84:85], v[68:69]
	v_mov_b64_e32 v[82:83], v[66:67]
	v_mov_b64_e32 v[80:81], v[64:65]
	s_waitcnt lgkmcnt(3)
	v_mfma_f32_32x32x16_bf16 v[96:111], v[152:155], v[112:115], v[96:111]
	v_mfma_f32_32x32x16_bf16 v[80:95], v[152:155], v[132:135], v[80:95]
	s_waitcnt lgkmcnt(2)
	v_mfma_f32_32x32x16_bf16 v[96:111], v[156:159], v[116:119], v[96:111]
	v_mfma_f32_32x32x16_bf16 v[80:95], v[156:159], v[136:139], v[80:95]
	s_waitcnt lgkmcnt(1)
	v_mfma_f32_32x32x16_bf16 v[96:111], v[160:163], v[124:127], v[96:111]
	v_mfma_f32_32x32x16_bf16 v[80:95], v[160:163], v[140:143], v[80:95]
	s_waitcnt lgkmcnt(0)
	v_mfma_f32_32x32x16_bf16 v[96:111], v[164:167], v[128:131], v[96:111]
	v_mfma_f32_32x32x16_bf16 v[80:95], v[164:167], v[144:147], v[80:95]
	s_setprio 0
	ds_read_b128 v[172:175], v229 offset:20480
	ds_read_b128 v[168:171], v230 offset:20480
	ds_read_b128 v[176:179], v227 offset:20480
	ds_read_b128 v[160:163], v227 offset:24576
	ds_read_b128 v[180:183], v228 offset:20480
	ds_read_b128 v[152:155], v227 offset:28672
	ds_read_b128 v[164:167], v228 offset:24576
	ds_read_b128 v[156:159], v228 offset:28672
	s_nop 1
	v_max_f32_e32 v65, v97, v97
	v_max_f32_e32 v66, v96, v96
	v_max_f32_e32 v65, v66, v65
	v_max3_f32 v65, v65, v98, v99
	v_max3_f32 v65, v65, v100, v101
	v_max3_f32 v65, v65, v102, v103
	v_max3_f32 v65, v65, v104, v105
	v_max3_f32 v65, v65, v106, v107
	v_max3_f32 v65, v65, v108, v109
	v_max3_f32 v65, v65, v110, v111
	v_mov_b32_e32 v66, v65
	s_nop 1
	v_permlane32_swap_b32_e32 v65, v66
	v_max_f32_e32 v66, v66, v66
	v_max_f32_e32 v65, v65, v65
	v_max_f32_e32 v65, v65, v66
	v_cmp_lt_f32_e32 vcc, s97, v65
	s_cbranch_vccz .LBB0_326
	v_max_f32_e32 v65, v65, v65
	v_max_f32_e32 v66, 0, v65
	v_exp_f32_e64 v65, -v66
	v_add_f32_e32 v231, v231, v66
	v_pk_add_f32 v[96:97], v[96:97], v[66:67] op_sel_hi:[1,0] neg_lo:[0,1] neg_hi:[0,1]
	v_pk_add_f32 v[98:99], v[98:99], v[66:67] op_sel_hi:[1,0] neg_lo:[0,1] neg_hi:[0,1]
	ds_write_b32 v222, v65
	v_pk_add_f32 v[100:101], v[100:101], v[66:67] op_sel_hi:[1,0] neg_lo:[0,1] neg_hi:[0,1]
	v_pk_add_f32 v[102:103], v[102:103], v[66:67] op_sel_hi:[1,0] neg_lo:[0,1] neg_hi:[0,1]
	v_pk_add_f32 v[104:105], v[104:105], v[66:67] op_sel_hi:[1,0] neg_lo:[0,1] neg_hi:[0,1]
	v_pk_add_f32 v[106:107], v[106:107], v[66:67] op_sel_hi:[1,0] neg_lo:[0,1] neg_hi:[0,1]
	v_pk_add_f32 v[108:109], v[108:109], v[66:67] op_sel_hi:[1,0] neg_lo:[0,1] neg_hi:[0,1]
	v_pk_add_f32 v[110:111], v[110:111], v[66:67] op_sel_hi:[1,0] neg_lo:[0,1] neg_hi:[0,1]
	ds_read_b128 v[66:69], v221
	ds_read_b128 v[70:73], v221 offset:32
	ds_read_b128 v[74:77], v221 offset:64
	ds_read_b128 v[236:239], v221 offset:96
	v_mul_f32_e32 v234, v234, v65
	s_waitcnt lgkmcnt(3)
	v_pk_mul_f32 v[50:51], v[50:51], v[68:69]
	s_waitcnt lgkmcnt(2)
	v_pk_mul_f32 v[54:55], v[54:55], v[72:73]
	s_waitcnt lgkmcnt(1)
	v_pk_mul_f32 v[58:59], v[58:59], v[76:77]
	s_waitcnt lgkmcnt(0)
	v_pk_mul_f32 v[62:63], v[62:63], v[238:239]
	v_pk_mul_f32 v[60:61], v[60:61], v[236:237]
	v_pk_mul_f32 v[56:57], v[56:57], v[74:75]
	v_pk_mul_f32 v[52:53], v[52:53], v[70:71]
	v_pk_mul_f32 v[48:49], v[48:49], v[66:67]
	v_pk_mul_f32 v[46:47], v[46:47], v[238:239]
	v_pk_mul_f32 v[42:43], v[42:43], v[76:77]
	v_pk_mul_f32 v[38:39], v[38:39], v[72:73]
	v_pk_mul_f32 v[34:35], v[34:35], v[68:69]
	v_pk_mul_f32 v[44:45], v[44:45], v[236:237]
	v_pk_mul_f32 v[40:41], v[40:41], v[74:75]
	v_pk_mul_f32 v[36:37], v[36:37], v[70:71]
	v_pk_mul_f32 v[32:33], v[32:33], v[66:67]
.LBB0_326:
	v_add_f32_e32 v66, v198, v200
	v_add_f32_e32 v67, v199, v201
	s_nop 0
	v_add_f32_e32 v66, v202, v66
	v_add_f32_e32 v67, v203, v67
	s_nop 0
	v_add_f32_e32 v66, v204, v66
	v_add_f32_e32 v67, v205, v67
	s_nop 0
	v_add_f32_e32 v66, v206, v66
	v_add_f32_e32 v67, v207, v67
	s_nop 0
	v_add_f32_e32 v66, v208, v66
	v_add_f32_e32 v67, v209, v67
	s_nop 0
	v_add_f32_e32 v66, v210, v66
	v_add_f32_e32 v67, v211, v67
	s_nop 0
	v_add_f32_e32 v66, v212, v66
	v_add_f32_e32 v67, v213, v67
	s_nop 0
	v_add_f32_e32 v65, v66, v67
	v_add_f32_e32 v232, v233, v65
	v_max_f32_e32 v65, v81, v81
	v_max_f32_e32 v66, v80, v80
	v_max_f32_e32 v65, v66, v65
	v_max3_f32 v65, v65, v82, v83
	v_max3_f32 v65, v65, v84, v85
	v_max3_f32 v65, v65, v86, v87
	v_max3_f32 v65, v65, v88, v89
	v_max3_f32 v65, v65, v90, v91
	v_max3_f32 v65, v65, v92, v93
	v_max3_f32 v65, v65, v94, v95
	v_mov_b32_e32 v66, v65
	s_nop 1
	v_permlane32_swap_b32_e32 v65, v66
	v_max_f32_e32 v66, v66, v66
	v_max_f32_e32 v65, v65, v65
	v_max_f32_e32 v65, v65, v66
	v_cmp_lt_f32_e32 vcc, s97, v65
	s_cbranch_vccz .LBB0_328
	v_max_f32_e32 v64, v65, v65
	v_max_f32_e32 v64, 0, v64
	v_add_f32_e32 v223, v223, v64
	v_pk_add_f32 v[80:81], v[80:81], v[64:65] op_sel_hi:[1,0] neg_lo:[0,1] neg_hi:[0,1]
	v_pk_add_f32 v[82:83], v[82:83], v[64:65] op_sel_hi:[1,0] neg_lo:[0,1] neg_hi:[0,1]
	v_pk_add_f32 v[84:85], v[84:85], v[64:65] op_sel_hi:[1,0] neg_lo:[0,1] neg_hi:[0,1]
	v_pk_add_f32 v[86:87], v[86:87], v[64:65] op_sel_hi:[1,0] neg_lo:[0,1] neg_hi:[0,1]
	v_pk_add_f32 v[88:89], v[88:89], v[64:65] op_sel_hi:[1,0] neg_lo:[0,1] neg_hi:[0,1]
	v_pk_add_f32 v[90:91], v[90:91], v[64:65] op_sel_hi:[1,0] neg_lo:[0,1] neg_hi:[0,1]
	v_pk_add_f32 v[92:93], v[92:93], v[64:65] op_sel_hi:[1,0] neg_lo:[0,1] neg_hi:[0,1]
	v_pk_add_f32 v[94:95], v[94:95], v[64:65] op_sel_hi:[1,0] neg_lo:[0,1] neg_hi:[0,1]
	v_exp_f32_e64 v64, -v64
	ds_write_b32 v222, v64
	v_mul_f32_e32 v232, v232, v64
	ds_read_b128 v[64:67], v221
	ds_read_b128 v[68:71], v221 offset:32
	ds_read_b128 v[72:75], v221 offset:64
	ds_read_b128 v[76:79], v221 offset:96
	s_waitcnt lgkmcnt(3)
	v_pk_mul_f32 v[18:19], v[18:19], v[66:67]
	s_waitcnt lgkmcnt(2)
	v_pk_mul_f32 v[22:23], v[22:23], v[70:71]
	s_waitcnt lgkmcnt(1)
	v_pk_mul_f32 v[26:27], v[26:27], v[74:75]
	s_waitcnt lgkmcnt(0)
	v_pk_mul_f32 v[30:31], v[30:31], v[78:79]
	v_pk_mul_f32 v[28:29], v[28:29], v[76:77]
	v_pk_mul_f32 v[24:25], v[24:25], v[72:73]
	v_pk_mul_f32 v[20:21], v[20:21], v[68:69]
	v_pk_mul_f32 v[16:17], v[16:17], v[64:65]
	v_pk_mul_f32 v[14:15], v[14:15], v[78:79]
	v_pk_mul_f32 v[10:11], v[10:11], v[74:75]
	v_pk_mul_f32 v[6:7], v[6:7], v[70:71]
	v_pk_mul_f32 v[2:3], v[2:3], v[66:67]
	v_pk_mul_f32 v[12:13], v[12:13], v[76:77]
	v_pk_mul_f32 v[8:9], v[8:9], v[72:73]
	v_pk_mul_f32 v[4:5], v[4:5], v[68:69]
	v_pk_mul_f32 v[0:1], v[0:1], v[64:65]
	v_xor_b32_e32 v64, 0x80000000, v223
.LBB0_328:
	v_exp_f32_e32 v66, v96
	v_exp_f32_e32 v67, v97
	v_exp_f32_e32 v68, v98
	v_exp_f32_e32 v69, v99
	v_exp_f32_e32 v70, v100
	v_exp_f32_e32 v71, v101
	v_exp_f32_e32 v72, v102
	v_exp_f32_e32 v73, v103
	v_exp_f32_e32 v74, v104
	v_exp_f32_e32 v75, v105
	v_exp_f32_e32 v76, v106
	v_exp_f32_e32 v77, v107
	v_add_f32_e32 v96, v68, v66
	v_add_f32_e32 v97, v69, v67
	v_exp_f32_e32 v78, v108
	v_exp_f32_e32 v79, v109
	v_add_f32_e32 v96, v70, v96
	v_add_f32_e32 v97, v71, v97
	v_exp_f32_e32 v104, v110
	v_exp_f32_e32 v105, v111
	v_add_f32_e32 v96, v72, v96
	v_add_f32_e32 v97, v73, v97
	v_exp_f32_e32 v198, v80
	v_add_f32_e32 v96, v74, v96
	v_add_f32_e32 v97, v75, v97
	v_exp_f32_e32 v199, v81
	v_add_f32_e32 v96, v76, v96
	v_add_f32_e32 v97, v77, v97
	v_exp_f32_e32 v200, v82
	v_exp_f32_e32 v201, v83
	v_exp_f32_e32 v202, v84
	v_exp_f32_e32 v203, v85
	v_exp_f32_e32 v204, v86
	v_exp_f32_e32 v205, v87
	v_exp_f32_e32 v206, v88
	v_exp_f32_e32 v207, v89
	v_exp_f32_e32 v208, v90
	v_exp_f32_e32 v209, v91
	v_exp_f32_e32 v210, v92
	v_exp_f32_e32 v211, v93
	v_exp_f32_e32 v212, v94
	v_exp_f32_e32 v213, v95
	v_add_f32_e32 v96, v78, v96
	v_add_f32_e32 v97, v79, v97
	v_cvt_pk_bf16_f32 v100, v74, v75
	v_add_f32_e32 v96, v104, v96
	v_add_f32_e32 v97, v105, v97
	v_cvt_pk_bf16_f32 v101, v76, v77
	v_add_f32_e32 v65, v96, v97
	v_add_f32_e32 v233, v234, v65
	v_cvt_pk_bf16_f32 v96, v66, v67
	v_cvt_pk_bf16_f32 v97, v68, v69
	v_cvt_pk_bf16_f32 v98, v70, v71
	v_cvt_pk_bf16_f32 v102, v78, v79
	v_cvt_pk_bf16_f32 v99, v72, v73
	v_cvt_pk_bf16_f32 v103, v104, v105
	v_mov_b32_e32 v65, v64
	v_mov_b32_e32 v66, v64
	v_mov_b32_e32 v67, v64
	v_mov_b32_e32 v68, v64
	v_mov_b32_e32 v69, v64
	v_mov_b32_e32 v70, v64
	v_mov_b32_e32 v71, v64
	v_mov_b32_e32 v72, v64
	v_mov_b32_e32 v73, v64
	v_mov_b32_e32 v74, v64
	v_mov_b32_e32 v75, v64
	v_mov_b32_e32 v76, v64
	v_mov_b32_e32 v77, v64
	v_mov_b32_e32 v78, v64
	v_mov_b32_e32 v79, v64
	v_cvt_pk_bf16_f32 v104, v198, v199
	v_cvt_pk_bf16_f32 v108, v206, v207
	v_cvt_pk_bf16_f32 v105, v200, v201
	v_cvt_pk_bf16_f32 v109, v208, v209
	v_cvt_pk_bf16_f32 v106, v202, v203
	v_cvt_pk_bf16_f32 v110, v210, v211
	v_cvt_pk_bf16_f32 v107, v204, v205
	v_cvt_pk_bf16_f32 v111, v212, v213
	v_xor_b32_e32 v80, 0x80000000, v231
	s_setprio 1
	v_mov_b32_e32 v81, v80
	v_mov_b32_e32 v82, v80
	v_mov_b32_e32 v83, v80
	v_mov_b32_e32 v84, v80
	v_mov_b32_e32 v85, v80
	v_mov_b32_e32 v86, v80
	v_mov_b32_e32 v87, v80
	v_mov_b32_e32 v88, v80
	v_mov_b32_e32 v89, v80
	v_mov_b32_e32 v90, v80
	v_mov_b32_e32 v91, v80
	v_mov_b32_e32 v92, v80
	v_mov_b32_e32 v93, v80
	v_mov_b32_e32 v94, v80
	v_mov_b32_e32 v95, v80
	s_waitcnt lgkmcnt(5)
	v_mfma_f32_32x32x16_bf16 v[64:79], v[176:179], v[132:135], v[64:79]
	v_mfma_f32_32x32x16_bf16 v[80:95], v[176:179], v[112:115], v[80:95]
	s_waitcnt lgkmcnt(3)
	v_mfma_f32_32x32x16_bf16 v[80:95], v[180:183], v[116:119], v[80:95]
	v_mfma_f32_32x32x16_bf16 v[64:79], v[180:183], v[136:139], v[64:79]
	v_mfma_f32_32x32x16_bf16 v[80:95], v[172:175], v[124:127], v[80:95]
	v_mfma_f32_32x32x16_bf16 v[64:79], v[172:175], v[140:143], v[64:79]
	v_mfma_f32_32x32x16_bf16 v[80:95], v[168:171], v[128:131], v[80:95]
	v_mfma_f32_32x32x16_bf16 v[64:79], v[168:171], v[144:147], v[64:79]
	s_setprio 0
	s_setprio 1
	v_mfma_f32_32x32x16_bf16 v[48:63], v[96:99], v[160:163], v[48:63]
	s_waitcnt lgkmcnt(2)
	v_mfma_f32_32x32x16_bf16 v[32:47], v[96:99], v[152:155], v[32:47]
	v_mfma_f32_32x32x16_bf16 v[16:31], v[104:107], v[160:163], v[16:31]
	v_mfma_f32_32x32x16_bf16 v[0:15], v[104:107], v[152:155], v[0:15]
	s_waitcnt lgkmcnt(1)
	v_mfma_f32_32x32x16_bf16 v[48:63], v[100:103], v[164:167], v[48:63]
	s_waitcnt lgkmcnt(0)
	v_mfma_f32_32x32x16_bf16 v[32:47], v[100:103], v[156:159], v[32:47]
	v_mfma_f32_32x32x16_bf16 v[16:31], v[108:111], v[164:167], v[16:31]
	v_mfma_f32_32x32x16_bf16 v[0:15], v[108:111], v[156:159], v[0:15]
	s_setprio 0
	ds_read_b128 v[104:107], v229 offset:24576
	ds_read_b128 v[96:99], v229 offset:28672
	ds_read_b128 v[108:111], v230 offset:24576
	ds_read_b128 v[100:103], v230 offset:28672
	v_max_f32_e32 v152, v81, v81
	v_max_f32_e32 v153, v80, v80
	v_max_f32_e32 v152, v153, v152
	v_max3_f32 v152, v152, v82, v83
	v_max3_f32 v152, v152, v84, v85
	v_max3_f32 v152, v152, v86, v87
	v_max3_f32 v152, v152, v88, v89
	v_max3_f32 v152, v152, v90, v91
	v_max3_f32 v152, v152, v92, v93
	v_max3_f32 v152, v152, v94, v95
	v_mov_b32_e32 v153, v152
	s_nop 1
	v_permlane32_swap_b32_e32 v152, v153
	v_max_f32_e32 v153, v153, v153
	v_max_f32_e32 v152, v152, v152
	v_max_f32_e32 v152, v152, v153
	v_cmp_lt_f32_e32 vcc, s97, v152
	s_cbranch_vccz .LBB0_330
	v_max_f32_e32 v152, v152, v152
	v_max_f32_e32 v152, 0, v152
	v_add_f32_e32 v231, v231, v152
	v_pk_add_f32 v[80:81], v[80:81], v[152:153] op_sel_hi:[1,0] neg_lo:[0,1] neg_hi:[0,1]
	v_pk_add_f32 v[82:83], v[82:83], v[152:153] op_sel_hi:[1,0] neg_lo:[0,1] neg_hi:[0,1]
	v_pk_add_f32 v[84:85], v[84:85], v[152:153] op_sel_hi:[1,0] neg_lo:[0,1] neg_hi:[0,1]
	v_pk_add_f32 v[86:87], v[86:87], v[152:153] op_sel_hi:[1,0] neg_lo:[0,1] neg_hi:[0,1]
	v_pk_add_f32 v[88:89], v[88:89], v[152:153] op_sel_hi:[1,0] neg_lo:[0,1] neg_hi:[0,1]
	v_pk_add_f32 v[90:91], v[90:91], v[152:153] op_sel_hi:[1,0] neg_lo:[0,1] neg_hi:[0,1]
	v_pk_add_f32 v[92:93], v[92:93], v[152:153] op_sel_hi:[1,0] neg_lo:[0,1] neg_hi:[0,1]
	v_pk_add_f32 v[94:95], v[94:95], v[152:153] op_sel_hi:[1,0] neg_lo:[0,1] neg_hi:[0,1]
	v_exp_f32_e64 v152, -v152
	ds_write_b32 v222, v152
	v_mul_f32_e32 v233, v233, v152
	ds_read_b128 v[152:155], v221
	ds_read_b128 v[156:159], v221 offset:32
	ds_read_b128 v[160:163], v221 offset:64
	ds_read_b128 v[164:167], v221 offset:96
	s_waitcnt lgkmcnt(3)
	v_pk_mul_f32 v[50:51], v[50:51], v[154:155]
	s_waitcnt lgkmcnt(2)
	v_pk_mul_f32 v[54:55], v[54:55], v[158:159]
	s_waitcnt lgkmcnt(1)
	v_pk_mul_f32 v[58:59], v[58:59], v[162:163]
	s_waitcnt lgkmcnt(0)
	v_pk_mul_f32 v[62:63], v[62:63], v[166:167]
	v_pk_mul_f32 v[60:61], v[60:61], v[164:165]
	v_pk_mul_f32 v[56:57], v[56:57], v[160:161]
	v_pk_mul_f32 v[52:53], v[52:53], v[156:157]
	v_pk_mul_f32 v[48:49], v[48:49], v[152:153]
	v_pk_mul_f32 v[46:47], v[46:47], v[166:167]
	v_pk_mul_f32 v[42:43], v[42:43], v[162:163]
	v_pk_mul_f32 v[38:39], v[38:39], v[158:159]
	v_pk_mul_f32 v[34:35], v[34:35], v[154:155]
	v_pk_mul_f32 v[44:45], v[44:45], v[164:165]
	v_pk_mul_f32 v[40:41], v[40:41], v[160:161]
	v_pk_mul_f32 v[36:37], v[36:37], v[156:157]
	v_pk_mul_f32 v[32:33], v[32:33], v[152:153]
.LBB0_330:
	v_add_f32_e32 v152, v198, v200
	v_add_f32_e32 v153, v199, v201
	v_max_f32_e32 v154, v64, v64
	v_add_f32_e32 v152, v202, v152
	v_add_f32_e32 v153, v203, v153
	s_nop 0
	v_add_f32_e32 v152, v204, v152
	v_add_f32_e32 v153, v205, v153
	s_nop 0
	v_add_f32_e32 v152, v206, v152
	v_add_f32_e32 v153, v207, v153
	s_nop 0
	v_add_f32_e32 v152, v208, v152
	v_add_f32_e32 v153, v209, v153
	s_nop 0
	v_add_f32_e32 v152, v210, v152
	v_add_f32_e32 v153, v211, v153
	s_nop 0
	v_add_f32_e32 v152, v212, v152
	v_add_f32_e32 v153, v213, v153
	s_nop 0
	v_add_f32_e32 v152, v152, v153
	v_max_f32_e32 v153, v65, v65
	v_max_f32_e32 v153, v154, v153
	v_max3_f32 v153, v153, v66, v67
	v_max3_f32 v153, v153, v68, v69
	v_max3_f32 v153, v153, v70, v71
	v_max3_f32 v153, v153, v72, v73
	v_max3_f32 v153, v153, v74, v75
	v_max3_f32 v153, v153, v76, v77
	v_max3_f32 v153, v153, v78, v79
	v_mov_b32_e32 v154, v153
	s_nop 1
	v_permlane32_swap_b32_e32 v153, v154
	v_max_f32_e32 v154, v154, v154
	v_max_f32_e32 v153, v153, v153
	v_max_f32_e32 v153, v153, v154
	v_add_f32_e32 v152, v232, v152
	v_cmp_lt_f32_e32 vcc, s97, v153
	s_cbranch_vccz .LBB0_301
	v_max_f32_e32 v153, v153, v153
	v_max_f32_e32 v154, 0, v153
	v_exp_f32_e64 v153, -v154
	v_add_f32_e32 v223, v223, v154
	v_pk_add_f32 v[64:65], v[64:65], v[154:155] op_sel_hi:[1,0] neg_lo:[0,1] neg_hi:[0,1]
	v_pk_add_f32 v[66:67], v[66:67], v[154:155] op_sel_hi:[1,0] neg_lo:[0,1] neg_hi:[0,1]
	ds_write_b32 v222, v153
	v_pk_add_f32 v[68:69], v[68:69], v[154:155] op_sel_hi:[1,0] neg_lo:[0,1] neg_hi:[0,1]
	v_pk_add_f32 v[70:71], v[70:71], v[154:155] op_sel_hi:[1,0] neg_lo:[0,1] neg_hi:[0,1]
	v_pk_add_f32 v[72:73], v[72:73], v[154:155] op_sel_hi:[1,0] neg_lo:[0,1] neg_hi:[0,1]
	v_pk_add_f32 v[74:75], v[74:75], v[154:155] op_sel_hi:[1,0] neg_lo:[0,1] neg_hi:[0,1]
	v_pk_add_f32 v[76:77], v[76:77], v[154:155] op_sel_hi:[1,0] neg_lo:[0,1] neg_hi:[0,1]
	v_pk_add_f32 v[78:79], v[78:79], v[154:155] op_sel_hi:[1,0] neg_lo:[0,1] neg_hi:[0,1]
	ds_read_b128 v[154:157], v221
	ds_read_b128 v[158:161], v221 offset:32
	ds_read_b128 v[162:165], v221 offset:64
	ds_read_b128 v[166:169], v221 offset:96
	v_mul_f32_e32 v152, v152, v153
	s_waitcnt lgkmcnt(3)
	v_pk_mul_f32 v[18:19], v[18:19], v[156:157]
	s_waitcnt lgkmcnt(2)
	v_pk_mul_f32 v[22:23], v[22:23], v[160:161]
	s_waitcnt lgkmcnt(1)
	v_pk_mul_f32 v[26:27], v[26:27], v[164:165]
	s_waitcnt lgkmcnt(0)
	v_pk_mul_f32 v[30:31], v[30:31], v[168:169]
	v_pk_mul_f32 v[28:29], v[28:29], v[166:167]
	v_pk_mul_f32 v[24:25], v[24:25], v[162:163]
	v_pk_mul_f32 v[20:21], v[20:21], v[158:159]
	v_pk_mul_f32 v[16:17], v[16:17], v[154:155]
	v_pk_mul_f32 v[14:15], v[14:15], v[168:169]
	v_pk_mul_f32 v[10:11], v[10:11], v[164:165]
	v_pk_mul_f32 v[6:7], v[6:7], v[160:161]
	v_pk_mul_f32 v[2:3], v[2:3], v[156:157]
	v_pk_mul_f32 v[12:13], v[12:13], v[166:167]
	v_pk_mul_f32 v[8:9], v[8:9], v[162:163]
	v_pk_mul_f32 v[4:5], v[4:5], v[158:159]
	v_pk_mul_f32 v[0:1], v[0:1], v[154:155]
	s_branch .LBB0_301
